# P7: use the non-fused path (EpiRes GEMM epilogue + separate FFN pre-norm row pass) instead of the fused cross-WG norm epilogue
# speedup vs baseline: 1.0020x; 1.0020x over previous
.LBB0_915:
	s_or_b64 exec, exec, s[0:1]
	s_cmpk_lg_i32 s90, 0x100
	s_cselect_b64 s[2:3], -1, 0
	s_add_u32 s46, s70, 0x2000
	s_addc_u32 s47, s71, 0
	s_cmpk_eq_i32 s90, 0x100
	s_mov_b64 s[0:1], -1
	s_waitcnt lgkmcnt(0)
	s_barrier
	s_nop 0
	v_readlane_b32 s0, v255, 16
	v_readlane_b32 s1, v255, 17
	s_and_b64 vcc, exec, s[0:1]
	v_mbcnt_lo_u32_b32 v9, -1, 0
	v_mbcnt_hi_u32_b32 v9, -1, v9
	s_cbranch_vccz .LBB0_936
	v_lshlrev_b32_e32 v0, 4, v9
	v_and_b32_e32 v0, 0x3f0, v0
	v_or_b32_e32 v0, s33, v0
	v_add_u32_e32 v1, 0x2000, v0
	v_ashrrev_i32_e32 v2, 31, v1
	v_lshrrev_b32_e32 v2, 22, v2
	v_add_u32_e32 v2, v1, v2
	v_ashrrev_i32_e32 v8, 10, v2
	v_mul_i32_i24_e32 v2, 0x400, v8
	v_sub_u32_e32 v1, v1, v2
	v_lshrrev_b32_e32 v2, 4, v1
	v_bitop3_b32 v1, v2, v1, 32 bitop3:0x6c
	v_ashrrev_i32_e32 v2, 31, v1
	v_lshrrev_b32_e32 v2, 26, v2
	v_add_u32_e32 v2, v1, v2
	v_ashrrev_i32_e32 v10, 6, v2
	v_lshlrev_b32_e32 v3, 3, v8
	v_and_b32_e32 v2, 0xffc0, v2
	v_and_b32_e32 v3, -16, v3
	v_sub_u32_e32 v1, v1, v2
	v_add_u32_e32 v3, v10, v3
	v_lshrrev_b16_e32 v2, 7, v1
	v_and_b32_e32 v4, 3, v10
	s_mov_b32 s0, 0x1fffe0
	v_lshrrev_b32_e32 v5, 2, v3
	v_lshlrev_b32_e32 v6, 1, v3
	v_and_b32_e32 v2, 1, v2
	v_and_or_b32 v4, v3, s0, v4
	v_and_b32_e32 v5, 4, v5
	v_and_b32_e32 v6, 24, v6
	v_add_u16_e32 v1, v1, v2
	v_mov_b32_e32 v2, 1
	v_or3_b32 v4, v4, v5, v6
	v_lshlrev_b32_e32 v5, 5, v8
	v_ashrrev_i16_sdwa v1, v2, sext(v1) dst_sel:DWORD dst_unused:UNUSED_PAD src0_sel:DWORD src1_sel:BYTE_0
	v_and_b32_e32 v5, 32, v5
	v_bfe_i32 v11, v1, 0, 16
	s_ashr_i32 s1, s33, 31
	v_add_lshl_u32 v1, v5, v11, 1
	s_lshr_b32 s1, s1, 22
	v_lshl_add_u32 v144, v4, 11, v1
	v_lshl_add_u32 v146, v3, 11, v1
	v_add_u32_e32 v1, s1, v0
	v_ashrrev_i32_e32 v12, 10, v1
	v_mul_i32_i24_e32 v1, 0x400, v12
	v_sub_u32_e32 v0, v0, v1
	v_lshrrev_b32_e32 v1, 4, v0
	v_bitop3_b32 v0, v1, v0, 32 bitop3:0x6c
	v_ashrrev_i32_e32 v1, 31, v0
	v_lshrrev_b32_e32 v1, 26, v1
	v_add_u32_e32 v1, v0, v1
	v_lshlrev_b32_e32 v3, 3, v12
	v_ashrrev_i32_e32 v13, 6, v1
	v_and_b32_e32 v3, -16, v3
	v_add_u32_e32 v3, v13, v3
	v_and_b32_e32 v4, 3, v13
	v_and_or_b32 v4, v3, s0, v4
	v_readlane_b32 s0, v255, 7
	s_lshr_b32 s0, s0, 29
	s_add_i32 s0, s57, s0
	s_and_b32 s1, s0, -8
	s_sub_i32 s1, s57, s1
	s_lshl_b32 s5, s1, 6
	s_ashr_i32 s0, s0, 3
	s_mul_i32 s4, s1, 0x41
	s_cmp_lt_i32 s1, 0
	s_cselect_b32 s1, s4, s5
	s_add_i32 s0, s1, s0
	s_ashr_i32 s1, s0, 31
	s_lshr_b32 s1, s1, 27
	s_add_i32 s1, s0, s1
	s_ashr_i32 s4, s1, 5
	s_andn2_b32 s1, s1, 31
	s_sub_i32 s1, s0, s1
	s_bfe_i32 s0, s1, 0x80000
	s_bfe_u32 s0, s0, 0x3000c
	s_add_i32 s5, s1, s0
	s_bfe_i32 s0, s5, 0x80000
	s_and_b32 s5, s5, 0xf8
	s_sub_i32 s1, s1, s5
	s_lshl_b32 s4, s4, 3
	s_sext_i32_i16 s0, s0
	s_sext_i32_i8 s1, s1
	v_lshrrev_b32_e32 v5, 2, v3
	v_lshlrev_b32_e32 v6, 1, v3
	v_and_b32_e32 v1, 0xc0, v1
	s_lshr_b32 s0, s0, 3
	s_add_i32 s20, s4, s1
	v_and_b32_e32 v5, 4, v5
	v_and_b32_e32 v6, 24, v6
	v_sub_u32_e32 v0, v0, v1
	s_ashr_i32 s21, s20, 31
	s_bfe_i64 s[6:7], s[0:1], 0x100000
	v_or3_b32 v4, v4, v5, v6
	v_lshlrev_b32_e32 v5, 5, v12
	v_ashrrev_i16_sdwa v0, v2, sext(v0) dst_sel:DWORD dst_unused:UNUSED_PAD src0_sel:DWORD src1_sel:BYTE_0
	s_lshl_b64 s[4:5], s[20:21], 19
	s_lshl_b64 s[6:7], s[6:7], 19
	v_readlane_b32 s8, v254, 27
	v_and_b32_e32 v5, 32, v5
	v_bfe_i32 v14, v0, 0, 16
	v_readlane_b32 s9, v254, 28
	s_add_u32 s24, s8, s6
	v_add_lshl_u32 v0, v5, v14, 1
	s_addc_u32 s25, s9, s7
	s_add_i32 s21, s33, 0
	v_lshl_add_u32 v148, v4, 11, v0
	s_add_i32 m0, s21, 0x10000
	v_lshl_add_u32 v150, v3, 11, v0
	global_load_lds_dwordx4 v148, s[24:25]
	s_add_i32 m0, s21, 0x12000
	s_add_u32 s6, s24, 0x40000
	global_load_lds_dwordx4 v144, s[24:25]
	s_addc_u32 s7, s25, 0
	s_add_i32 m0, s21, 0x14000
	v_mov_b32_e32 v149, 0
	global_load_lds_dwordx4 v148, s[6:7]
	s_add_i32 m0, s21, 0x16000
	s_add_u32 s22, s88, s4
	s_addc_u32 s23, s89, s5
	s_add_i32 s28, s21, 0x2000
	global_load_lds_dwordx4 v144, s[6:7]
	s_mov_b32 m0, s21
	s_add_u32 s4, s22, 0x40000
	global_load_lds_dwordx4 v150, s[22:23]
	s_mov_b32 m0, s28
	s_addc_u32 s5, s23, 0
	s_add_i32 s29, s21, 0x4000
	global_load_lds_dwordx4 v146, s[22:23]
	s_mov_b32 m0, s29
	s_add_i32 s30, s21, 0x6000
	global_load_lds_dwordx4 v150, s[4:5]
	s_mov_b32 m0, s30
	v_readlane_b32 s6, v255, 2
	global_load_lds_dwordx4 v146, s[4:5]
	v_readlane_b32 s7, v255, 3
	v_mov_b32_e32 v145, v149
	v_mov_b32_e32 v151, v149
	v_mov_b32_e32 v147, v149
	v_cndmask_b32_e64 v6, 0, 1, s[6:7]
	s_mov_b32 s31, 0
	v_lshl_add_u64 v[4:5], s[24:25], 0, v[148:149]
	v_lshl_add_u64 v[2:3], s[24:25], 0, v[144:145]
	v_lshl_add_u64 v[0:1], s[22:23], 0, v[150:151]
	v_cmp_ne_u32_e64 s[4:5], 1, v6
	s_andn2_b64 vcc, exec, s[6:7]
	v_lshl_add_u64 v[6:7], s[22:23], 0, v[146:147]
	s_cbranch_vccnz .LBB0_919
	s_barrier
